# merge phase EpiGated<0> epilogue rewritten by hand: 16 G loads in flight, counted vmcnt
# speedup vs baseline: 1.0017x; 1.0005x over previous
.LBB0_207:
	s_and_b64 vcc, exec, s[42:43]
	s_cbranch_vccz .LBB0_209
	s_lshl_b32 s14, s64, 8
	v_mbcnt_lo_u32_b32 v96, -1, 0
	v_mbcnt_hi_u32_b32 v96, -1, v96
	s_lshl_b32 s16, s62, 8
	v_lshrrev_b32_e32 v130, 1, v96
	s_add_i32 s14, s14, s71
	v_and_or_b32 v130, v130, 24, s16
	v_and_or_b32 v134, v96, 15, s14
	v_or_b32_e32 v132, s91, v130
	v_ashrrev_i32_e32 v135, 31, v134
	v_ashrrev_i32_e32 v133, 31, v132
	v_lshlrev_b64 v[130:131], 10, v[134:135]
	v_lshl_add_u64 v[130:131], v[130:131], 0, v[132:133]
	v_lshl_add_u64 v[164:165], s[88:89], 0, v[130:131]
	v_lshl_add_u64 v[204:205], v[130:131], 1, s[94:95]
	s_mov_b32 s101, 0
	global_load_dwordx2 v[220:221], v[164:165], off
	global_load_dwordx2 v[222:223], v[164:165], off offset:128
	s_mov_b32 s100, 0x4000
	v_lshl_add_u64 v[164:165], s[100:101], 0, v[164:165]
	global_load_dwordx2 v[224:225], v[164:165], off
	global_load_dwordx2 v[226:227], v[164:165], off offset:128
	s_mov_b32 s100, 0x4000
	v_lshl_add_u64 v[164:165], s[100:101], 0, v[164:165]
	global_load_dwordx2 v[228:229], v[164:165], off
	global_load_dwordx2 v[230:231], v[164:165], off offset:128
	s_mov_b32 s100, 0x4000
	v_lshl_add_u64 v[164:165], s[100:101], 0, v[164:165]
	global_load_dwordx2 v[232:233], v[164:165], off
	global_load_dwordx2 v[234:235], v[164:165], off offset:128
	s_mov_b32 s100, 0x14000
	v_lshl_add_u64 v[164:165], s[100:101], 0, v[164:165]
	global_load_dwordx2 v[236:237], v[164:165], off
	global_load_dwordx2 v[238:239], v[164:165], off offset:128
	s_mov_b32 s100, 0x4000
	v_lshl_add_u64 v[164:165], s[100:101], 0, v[164:165]
	global_load_dwordx2 v[240:241], v[164:165], off
	global_load_dwordx2 v[242:243], v[164:165], off offset:128
	s_mov_b32 s100, 0x4000
	v_lshl_add_u64 v[164:165], s[100:101], 0, v[164:165]
	global_load_dwordx2 v[244:245], v[164:165], off
	global_load_dwordx2 v[246:247], v[164:165], off offset:128
	s_mov_b32 s100, 0x4000
	v_lshl_add_u64 v[164:165], s[100:101], 0, v[164:165]
	global_load_dwordx2 v[248:249], v[164:165], off
	global_load_dwordx2 v[250:251], v[164:165], off offset:128
	s_mov_b32 s100, 0x8000
	v_lshl_add_u64 v[206:207], s[100:101], 0, v[204:205]
	s_mov_b32 s100, 0x8000
	v_lshl_add_u64 v[208:209], s[100:101], 0, v[206:207]
	s_mov_b32 s100, 0x8000
	v_lshl_add_u64 v[210:211], s[100:101], 0, v[208:209]
	s_mov_b32 s100, 0x28000
	v_lshl_add_u64 v[212:213], s[100:101], 0, v[210:211]
	s_mov_b32 s100, 0x8000
	v_lshl_add_u64 v[158:159], s[100:101], 0, v[212:213]
	s_mov_b32 s100, 0x8000
	v_lshl_add_u64 v[160:161], s[100:101], 0, v[158:159]
	s_mov_b32 s100, 0x8000
	v_lshl_add_u64 v[162:163], s[100:101], 0, v[160:161]
	s_waitcnt vmcnt(15)
	v_cvt_f32_ubyte0_e32 v130, v220
	v_cvt_f32_ubyte1_e32 v131, v220
	v_cvt_f32_ubyte2_e32 v132, v220
	v_cvt_f32_ubyte3_e32 v133, v220
	v_cvt_f32_ubyte0_e32 v134, v221
	v_cvt_f32_ubyte1_e32 v135, v221
	v_cvt_f32_ubyte2_e32 v136, v221
	v_cvt_f32_ubyte3_e32 v137, v221
	v_pk_mul_f32 v[130:131], v[130:131], s[34:35] op_sel_hi:[1,0]
	v_pk_mul_f32 v[132:133], v[132:133], s[34:35] op_sel_hi:[1,0]
	v_pk_mul_f32 v[134:135], v[134:135], s[34:35] op_sel_hi:[1,0]
	v_pk_mul_f32 v[136:137], v[136:137], s[34:35] op_sel_hi:[1,0]
	v_pk_mul_f32 v[130:131], v[126:127], v[130:131]
	v_pk_mul_f32 v[132:133], v[128:129], v[132:133]
	v_pk_mul_f32 v[134:135], v[122:123], v[134:135]
	v_pk_mul_f32 v[136:137], v[124:125], v[136:137]
	v_cvt_pk_bf16_f32 v150, v130, v131
	v_cvt_pk_bf16_f32 v151, v132, v133
	v_cvt_pk_bf16_f32 v152, v134, v135
	v_cvt_pk_bf16_f32 v153, v136, v137
	global_store_dwordx4 v[204:205], v[150:153], off
	s_waitcnt vmcnt(15)
	v_cvt_f32_ubyte0_e32 v130, v222
	v_cvt_f32_ubyte1_e32 v131, v222
	v_cvt_f32_ubyte2_e32 v132, v222
	v_cvt_f32_ubyte3_e32 v133, v222
	v_cvt_f32_ubyte0_e32 v134, v223
	v_cvt_f32_ubyte1_e32 v135, v223
	v_cvt_f32_ubyte2_e32 v136, v223
	v_cvt_f32_ubyte3_e32 v137, v223
	v_pk_mul_f32 v[130:131], v[130:131], s[34:35] op_sel_hi:[1,0]
	v_pk_mul_f32 v[132:133], v[132:133], s[34:35] op_sel_hi:[1,0]
	v_pk_mul_f32 v[134:135], v[134:135], s[34:35] op_sel_hi:[1,0]
	v_pk_mul_f32 v[136:137], v[136:137], s[34:35] op_sel_hi:[1,0]
	v_pk_mul_f32 v[130:131], v[118:119], v[130:131]
	v_pk_mul_f32 v[132:133], v[120:121], v[132:133]
	v_pk_mul_f32 v[134:135], v[114:115], v[134:135]
	v_pk_mul_f32 v[136:137], v[116:117], v[136:137]
	v_cvt_pk_bf16_f32 v154, v130, v131
	v_cvt_pk_bf16_f32 v155, v132, v133
	v_cvt_pk_bf16_f32 v156, v134, v135
	v_cvt_pk_bf16_f32 v157, v136, v137
	global_store_dwordx4 v[204:205], v[154:157], off offset:256
	s_waitcnt vmcnt(15)
	v_cvt_f32_ubyte0_e32 v130, v224
	v_cvt_f32_ubyte1_e32 v131, v224
	v_cvt_f32_ubyte2_e32 v132, v224
	v_cvt_f32_ubyte3_e32 v133, v224
	v_cvt_f32_ubyte0_e32 v134, v225
	v_cvt_f32_ubyte1_e32 v135, v225
	v_cvt_f32_ubyte2_e32 v136, v225
	v_cvt_f32_ubyte3_e32 v137, v225
	v_pk_mul_f32 v[130:131], v[130:131], s[34:35] op_sel_hi:[1,0]
	v_pk_mul_f32 v[132:133], v[132:133], s[34:35] op_sel_hi:[1,0]
	v_pk_mul_f32 v[134:135], v[134:135], s[34:35] op_sel_hi:[1,0]
	v_pk_mul_f32 v[136:137], v[136:137], s[34:35] op_sel_hi:[1,0]
	v_pk_mul_f32 v[130:131], v[110:111], v[130:131]
	v_pk_mul_f32 v[132:133], v[112:113], v[132:133]
	v_pk_mul_f32 v[134:135], v[106:107], v[134:135]
	v_pk_mul_f32 v[136:137], v[108:109], v[136:137]
	v_cvt_pk_bf16_f32 v150, v130, v131
	v_cvt_pk_bf16_f32 v151, v132, v133
	v_cvt_pk_bf16_f32 v152, v134, v135
	v_cvt_pk_bf16_f32 v153, v136, v137
	global_store_dwordx4 v[206:207], v[150:153], off
	s_waitcnt vmcnt(15)
	v_cvt_f32_ubyte0_e32 v130, v226
	v_cvt_f32_ubyte1_e32 v131, v226
	v_cvt_f32_ubyte2_e32 v132, v226
	v_cvt_f32_ubyte3_e32 v133, v226
	v_cvt_f32_ubyte0_e32 v134, v227
	v_cvt_f32_ubyte1_e32 v135, v227
	v_cvt_f32_ubyte2_e32 v136, v227
	v_cvt_f32_ubyte3_e32 v137, v227
	v_pk_mul_f32 v[130:131], v[130:131], s[34:35] op_sel_hi:[1,0]
	v_pk_mul_f32 v[132:133], v[132:133], s[34:35] op_sel_hi:[1,0]
	v_pk_mul_f32 v[134:135], v[134:135], s[34:35] op_sel_hi:[1,0]
	v_pk_mul_f32 v[136:137], v[136:137], s[34:35] op_sel_hi:[1,0]
	v_pk_mul_f32 v[130:131], v[102:103], v[130:131]
	v_pk_mul_f32 v[132:133], v[104:105], v[132:133]
	v_pk_mul_f32 v[134:135], v[98:99], v[134:135]
	v_pk_mul_f32 v[136:137], v[100:101], v[136:137]
	v_cvt_pk_bf16_f32 v154, v130, v131
	v_cvt_pk_bf16_f32 v155, v132, v133
	v_cvt_pk_bf16_f32 v156, v134, v135
	v_cvt_pk_bf16_f32 v157, v136, v137
	global_store_dwordx4 v[206:207], v[154:157], off offset:256
	s_waitcnt vmcnt(15)
	v_cvt_f32_ubyte0_e32 v130, v228
	v_cvt_f32_ubyte1_e32 v131, v228
	v_cvt_f32_ubyte2_e32 v132, v228
	v_cvt_f32_ubyte3_e32 v133, v228
	v_cvt_f32_ubyte0_e32 v134, v229
	v_cvt_f32_ubyte1_e32 v135, v229
	v_cvt_f32_ubyte2_e32 v136, v229
	v_cvt_f32_ubyte3_e32 v137, v229
	v_pk_mul_f32 v[130:131], v[130:131], s[34:35] op_sel_hi:[1,0]
	v_pk_mul_f32 v[132:133], v[132:133], s[34:35] op_sel_hi:[1,0]
	v_pk_mul_f32 v[134:135], v[134:135], s[34:35] op_sel_hi:[1,0]
	v_pk_mul_f32 v[136:137], v[136:137], s[34:35] op_sel_hi:[1,0]
	v_pk_mul_f32 v[130:131], v[92:93], v[130:131]
	v_pk_mul_f32 v[132:133], v[94:95], v[132:133]
	v_pk_mul_f32 v[134:135], v[88:89], v[134:135]
	v_pk_mul_f32 v[136:137], v[90:91], v[136:137]
	v_cvt_pk_bf16_f32 v150, v130, v131
	v_cvt_pk_bf16_f32 v151, v132, v133
	v_cvt_pk_bf16_f32 v152, v134, v135
	v_cvt_pk_bf16_f32 v153, v136, v137
	global_store_dwordx4 v[208:209], v[150:153], off
	s_waitcnt vmcnt(15)
	v_cvt_f32_ubyte0_e32 v130, v230
	v_cvt_f32_ubyte1_e32 v131, v230
	v_cvt_f32_ubyte2_e32 v132, v230
	v_cvt_f32_ubyte3_e32 v133, v230
	v_cvt_f32_ubyte0_e32 v134, v231
	v_cvt_f32_ubyte1_e32 v135, v231
	v_cvt_f32_ubyte2_e32 v136, v231
	v_cvt_f32_ubyte3_e32 v137, v231
	v_pk_mul_f32 v[130:131], v[130:131], s[34:35] op_sel_hi:[1,0]
	v_pk_mul_f32 v[132:133], v[132:133], s[34:35] op_sel_hi:[1,0]
	v_pk_mul_f32 v[134:135], v[134:135], s[34:35] op_sel_hi:[1,0]
	v_pk_mul_f32 v[136:137], v[136:137], s[34:35] op_sel_hi:[1,0]
	v_pk_mul_f32 v[130:131], v[84:85], v[130:131]
	v_pk_mul_f32 v[132:133], v[86:87], v[132:133]
	v_pk_mul_f32 v[134:135], v[80:81], v[134:135]
	v_pk_mul_f32 v[136:137], v[82:83], v[136:137]
	v_cvt_pk_bf16_f32 v154, v130, v131
	v_cvt_pk_bf16_f32 v155, v132, v133
	v_cvt_pk_bf16_f32 v156, v134, v135
	v_cvt_pk_bf16_f32 v157, v136, v137
	global_store_dwordx4 v[208:209], v[154:157], off offset:256
	s_waitcnt vmcnt(15)
	v_cvt_f32_ubyte0_e32 v130, v232
	v_cvt_f32_ubyte1_e32 v131, v232
	v_cvt_f32_ubyte2_e32 v132, v232
	v_cvt_f32_ubyte3_e32 v133, v232
	v_cvt_f32_ubyte0_e32 v134, v233
	v_cvt_f32_ubyte1_e32 v135, v233
	v_cvt_f32_ubyte2_e32 v136, v233
	v_cvt_f32_ubyte3_e32 v137, v233
	v_pk_mul_f32 v[130:131], v[130:131], s[34:35] op_sel_hi:[1,0]
	v_pk_mul_f32 v[132:133], v[132:133], s[34:35] op_sel_hi:[1,0]
	v_pk_mul_f32 v[134:135], v[134:135], s[34:35] op_sel_hi:[1,0]
	v_pk_mul_f32 v[136:137], v[136:137], s[34:35] op_sel_hi:[1,0]
	v_pk_mul_f32 v[130:131], v[76:77], v[130:131]
	v_pk_mul_f32 v[132:133], v[78:79], v[132:133]
	v_pk_mul_f32 v[134:135], v[72:73], v[134:135]
	v_pk_mul_f32 v[136:137], v[74:75], v[136:137]
	v_cvt_pk_bf16_f32 v150, v130, v131
	v_cvt_pk_bf16_f32 v151, v132, v133
	v_cvt_pk_bf16_f32 v152, v134, v135
	v_cvt_pk_bf16_f32 v153, v136, v137
	global_store_dwordx4 v[210:211], v[150:153], off
	s_waitcnt vmcnt(15)
	v_cvt_f32_ubyte0_e32 v130, v234
	v_cvt_f32_ubyte1_e32 v131, v234
	v_cvt_f32_ubyte2_e32 v132, v234
	v_cvt_f32_ubyte3_e32 v133, v234
	v_cvt_f32_ubyte0_e32 v134, v235
	v_cvt_f32_ubyte1_e32 v135, v235
	v_cvt_f32_ubyte2_e32 v136, v235
	v_cvt_f32_ubyte3_e32 v137, v235
	v_pk_mul_f32 v[130:131], v[130:131], s[34:35] op_sel_hi:[1,0]
	v_pk_mul_f32 v[132:133], v[132:133], s[34:35] op_sel_hi:[1,0]
	v_pk_mul_f32 v[134:135], v[134:135], s[34:35] op_sel_hi:[1,0]
	v_pk_mul_f32 v[136:137], v[136:137], s[34:35] op_sel_hi:[1,0]
	v_pk_mul_f32 v[130:131], v[68:69], v[130:131]
	v_pk_mul_f32 v[132:133], v[70:71], v[132:133]
	v_pk_mul_f32 v[134:135], v[64:65], v[134:135]
	v_pk_mul_f32 v[136:137], v[66:67], v[136:137]
	v_cvt_pk_bf16_f32 v154, v130, v131
	v_cvt_pk_bf16_f32 v155, v132, v133
	v_cvt_pk_bf16_f32 v156, v134, v135
	v_cvt_pk_bf16_f32 v157, v136, v137
	global_store_dwordx4 v[210:211], v[154:157], off offset:256
	s_waitcnt vmcnt(15)
	v_cvt_f32_ubyte0_e32 v130, v236
	v_cvt_f32_ubyte1_e32 v131, v236
	v_cvt_f32_ubyte2_e32 v132, v236
	v_cvt_f32_ubyte3_e32 v133, v236
	v_cvt_f32_ubyte0_e32 v134, v237
	v_cvt_f32_ubyte1_e32 v135, v237
	v_cvt_f32_ubyte2_e32 v136, v237
	v_cvt_f32_ubyte3_e32 v137, v237
	v_pk_mul_f32 v[130:131], v[130:131], s[34:35] op_sel_hi:[1,0]
	v_pk_mul_f32 v[132:133], v[132:133], s[34:35] op_sel_hi:[1,0]
	v_pk_mul_f32 v[134:135], v[134:135], s[34:35] op_sel_hi:[1,0]
	v_pk_mul_f32 v[136:137], v[136:137], s[34:35] op_sel_hi:[1,0]
	v_pk_mul_f32 v[130:131], v[60:61], v[130:131]
	v_pk_mul_f32 v[132:133], v[62:63], v[132:133]
	v_pk_mul_f32 v[134:135], v[56:57], v[134:135]
	v_pk_mul_f32 v[136:137], v[58:59], v[136:137]
	v_cvt_pk_bf16_f32 v150, v130, v131
	v_cvt_pk_bf16_f32 v151, v132, v133
	v_cvt_pk_bf16_f32 v152, v134, v135
	v_cvt_pk_bf16_f32 v153, v136, v137
	global_store_dwordx4 v[212:213], v[150:153], off
	s_waitcnt vmcnt(15)
	v_cvt_f32_ubyte0_e32 v130, v238
	v_cvt_f32_ubyte1_e32 v131, v238
	v_cvt_f32_ubyte2_e32 v132, v238
	v_cvt_f32_ubyte3_e32 v133, v238
	v_cvt_f32_ubyte0_e32 v134, v239
	v_cvt_f32_ubyte1_e32 v135, v239
	v_cvt_f32_ubyte2_e32 v136, v239
	v_cvt_f32_ubyte3_e32 v137, v239
	v_pk_mul_f32 v[130:131], v[130:131], s[34:35] op_sel_hi:[1,0]
	v_pk_mul_f32 v[132:133], v[132:133], s[34:35] op_sel_hi:[1,0]
	v_pk_mul_f32 v[134:135], v[134:135], s[34:35] op_sel_hi:[1,0]
	v_pk_mul_f32 v[136:137], v[136:137], s[34:35] op_sel_hi:[1,0]
	v_pk_mul_f32 v[130:131], v[52:53], v[130:131]
	v_pk_mul_f32 v[132:133], v[54:55], v[132:133]
	v_pk_mul_f32 v[134:135], v[48:49], v[134:135]
	v_pk_mul_f32 v[136:137], v[50:51], v[136:137]
	v_cvt_pk_bf16_f32 v154, v130, v131
	v_cvt_pk_bf16_f32 v155, v132, v133
	v_cvt_pk_bf16_f32 v156, v134, v135
	v_cvt_pk_bf16_f32 v157, v136, v137
	global_store_dwordx4 v[212:213], v[154:157], off offset:256
	s_waitcnt vmcnt(15)
	v_cvt_f32_ubyte0_e32 v130, v240
	v_cvt_f32_ubyte1_e32 v131, v240
	v_cvt_f32_ubyte2_e32 v132, v240
	v_cvt_f32_ubyte3_e32 v133, v240
	v_cvt_f32_ubyte0_e32 v134, v241
	v_cvt_f32_ubyte1_e32 v135, v241
	v_cvt_f32_ubyte2_e32 v136, v241
	v_cvt_f32_ubyte3_e32 v137, v241
	v_pk_mul_f32 v[130:131], v[130:131], s[34:35] op_sel_hi:[1,0]
	v_pk_mul_f32 v[132:133], v[132:133], s[34:35] op_sel_hi:[1,0]
	v_pk_mul_f32 v[134:135], v[134:135], s[34:35] op_sel_hi:[1,0]
	v_pk_mul_f32 v[136:137], v[136:137], s[34:35] op_sel_hi:[1,0]
	v_pk_mul_f32 v[130:131], v[44:45], v[130:131]
	v_pk_mul_f32 v[132:133], v[46:47], v[132:133]
	v_pk_mul_f32 v[134:135], v[40:41], v[134:135]
	v_pk_mul_f32 v[136:137], v[42:43], v[136:137]
	v_cvt_pk_bf16_f32 v150, v130, v131
	v_cvt_pk_bf16_f32 v151, v132, v133
	v_cvt_pk_bf16_f32 v152, v134, v135
	v_cvt_pk_bf16_f32 v153, v136, v137
	global_store_dwordx4 v[158:159], v[150:153], off
	s_waitcnt vmcnt(15)
	v_cvt_f32_ubyte0_e32 v130, v242
	v_cvt_f32_ubyte1_e32 v131, v242
	v_cvt_f32_ubyte2_e32 v132, v242
	v_cvt_f32_ubyte3_e32 v133, v242
	v_cvt_f32_ubyte0_e32 v134, v243
	v_cvt_f32_ubyte1_e32 v135, v243
	v_cvt_f32_ubyte2_e32 v136, v243
	v_cvt_f32_ubyte3_e32 v137, v243
	v_pk_mul_f32 v[130:131], v[130:131], s[34:35] op_sel_hi:[1,0]
	v_pk_mul_f32 v[132:133], v[132:133], s[34:35] op_sel_hi:[1,0]
	v_pk_mul_f32 v[134:135], v[134:135], s[34:35] op_sel_hi:[1,0]
	v_pk_mul_f32 v[136:137], v[136:137], s[34:35] op_sel_hi:[1,0]
	v_pk_mul_f32 v[130:131], v[36:37], v[130:131]
	v_pk_mul_f32 v[132:133], v[38:39], v[132:133]
	v_pk_mul_f32 v[134:135], v[32:33], v[134:135]
	v_pk_mul_f32 v[136:137], v[34:35], v[136:137]
	v_cvt_pk_bf16_f32 v154, v130, v131
	v_cvt_pk_bf16_f32 v155, v132, v133
	v_cvt_pk_bf16_f32 v156, v134, v135
	v_cvt_pk_bf16_f32 v157, v136, v137
	global_store_dwordx4 v[158:159], v[154:157], off offset:256
	s_waitcnt vmcnt(15)
	v_cvt_f32_ubyte0_e32 v130, v244
	v_cvt_f32_ubyte1_e32 v131, v244
	v_cvt_f32_ubyte2_e32 v132, v244
	v_cvt_f32_ubyte3_e32 v133, v244
	v_cvt_f32_ubyte0_e32 v134, v245
	v_cvt_f32_ubyte1_e32 v135, v245
	v_cvt_f32_ubyte2_e32 v136, v245
	v_cvt_f32_ubyte3_e32 v137, v245
	v_pk_mul_f32 v[130:131], v[130:131], s[34:35] op_sel_hi:[1,0]
	v_pk_mul_f32 v[132:133], v[132:133], s[34:35] op_sel_hi:[1,0]
	v_pk_mul_f32 v[134:135], v[134:135], s[34:35] op_sel_hi:[1,0]
	v_pk_mul_f32 v[136:137], v[136:137], s[34:35] op_sel_hi:[1,0]
	v_pk_mul_f32 v[130:131], v[28:29], v[130:131]
	v_pk_mul_f32 v[132:133], v[30:31], v[132:133]
	v_pk_mul_f32 v[134:135], v[24:25], v[134:135]
	v_pk_mul_f32 v[136:137], v[26:27], v[136:137]
	v_cvt_pk_bf16_f32 v150, v130, v131
	v_cvt_pk_bf16_f32 v151, v132, v133
	v_cvt_pk_bf16_f32 v152, v134, v135
	v_cvt_pk_bf16_f32 v153, v136, v137
	global_store_dwordx4 v[160:161], v[150:153], off
	s_waitcnt vmcnt(15)
	v_cvt_f32_ubyte0_e32 v130, v246
	v_cvt_f32_ubyte1_e32 v131, v246
	v_cvt_f32_ubyte2_e32 v132, v246
	v_cvt_f32_ubyte3_e32 v133, v246
	v_cvt_f32_ubyte0_e32 v134, v247
	v_cvt_f32_ubyte1_e32 v135, v247
	v_cvt_f32_ubyte2_e32 v136, v247
	v_cvt_f32_ubyte3_e32 v137, v247
	v_pk_mul_f32 v[130:131], v[130:131], s[34:35] op_sel_hi:[1,0]
	v_pk_mul_f32 v[132:133], v[132:133], s[34:35] op_sel_hi:[1,0]
	v_pk_mul_f32 v[134:135], v[134:135], s[34:35] op_sel_hi:[1,0]
	v_pk_mul_f32 v[136:137], v[136:137], s[34:35] op_sel_hi:[1,0]
	v_pk_mul_f32 v[130:131], v[20:21], v[130:131]
	v_pk_mul_f32 v[132:133], v[22:23], v[132:133]
	v_pk_mul_f32 v[134:135], v[16:17], v[134:135]
	v_pk_mul_f32 v[136:137], v[18:19], v[136:137]
	v_cvt_pk_bf16_f32 v154, v130, v131
	v_cvt_pk_bf16_f32 v155, v132, v133
	v_cvt_pk_bf16_f32 v156, v134, v135
	v_cvt_pk_bf16_f32 v157, v136, v137
	global_store_dwordx4 v[160:161], v[154:157], off offset:256
	s_waitcnt vmcnt(15)
	v_cvt_f32_ubyte0_e32 v130, v248
	v_cvt_f32_ubyte1_e32 v131, v248
	v_cvt_f32_ubyte2_e32 v132, v248
	v_cvt_f32_ubyte3_e32 v133, v248
	v_cvt_f32_ubyte0_e32 v134, v249
	v_cvt_f32_ubyte1_e32 v135, v249
	v_cvt_f32_ubyte2_e32 v136, v249
	v_cvt_f32_ubyte3_e32 v137, v249
	v_pk_mul_f32 v[130:131], v[130:131], s[34:35] op_sel_hi:[1,0]
	v_pk_mul_f32 v[132:133], v[132:133], s[34:35] op_sel_hi:[1,0]
	v_pk_mul_f32 v[134:135], v[134:135], s[34:35] op_sel_hi:[1,0]
	v_pk_mul_f32 v[136:137], v[136:137], s[34:35] op_sel_hi:[1,0]
	v_pk_mul_f32 v[130:131], v[12:13], v[130:131]
	v_pk_mul_f32 v[132:133], v[14:15], v[132:133]
	v_pk_mul_f32 v[134:135], v[8:9], v[134:135]
	v_pk_mul_f32 v[136:137], v[10:11], v[136:137]
	v_cvt_pk_bf16_f32 v150, v130, v131
	v_cvt_pk_bf16_f32 v151, v132, v133
	v_cvt_pk_bf16_f32 v152, v134, v135
	v_cvt_pk_bf16_f32 v153, v136, v137
	global_store_dwordx4 v[162:163], v[150:153], off
	s_waitcnt vmcnt(15)
	v_cvt_f32_ubyte0_e32 v130, v250
	v_cvt_f32_ubyte1_e32 v131, v250
	v_cvt_f32_ubyte2_e32 v132, v250
	v_cvt_f32_ubyte3_e32 v133, v250
	v_cvt_f32_ubyte0_e32 v134, v251
	v_cvt_f32_ubyte1_e32 v135, v251
	v_cvt_f32_ubyte2_e32 v136, v251
	v_cvt_f32_ubyte3_e32 v137, v251
	v_pk_mul_f32 v[130:131], v[130:131], s[34:35] op_sel_hi:[1,0]
	v_pk_mul_f32 v[132:133], v[132:133], s[34:35] op_sel_hi:[1,0]
	v_pk_mul_f32 v[134:135], v[134:135], s[34:35] op_sel_hi:[1,0]
	v_pk_mul_f32 v[136:137], v[136:137], s[34:35] op_sel_hi:[1,0]
	v_pk_mul_f32 v[130:131], v[4:5], v[130:131]
	v_pk_mul_f32 v[132:133], v[6:7], v[132:133]
	v_pk_mul_f32 v[134:135], v[0:1], v[134:135]
	v_pk_mul_f32 v[136:137], v[2:3], v[136:137]
	v_cvt_pk_bf16_f32 v154, v130, v131
	v_cvt_pk_bf16_f32 v155, v132, v133
	v_cvt_pk_bf16_f32 v156, v134, v135
	v_cvt_pk_bf16_f32 v157, v136, v137
	global_store_dwordx4 v[162:163], v[154:157], off offset:256
